# MoBA PV waves issue next-block V loads interleaved with the MFMAs of the block's first step instead of a burst at block start
# speedup vs baseline: 1.0935x; 1.0109x over previous
; #define LAS __attribute__((address_space(3)))
;     ...
;         const int ptt = wid >> 1, dh = wid & 1;
;         bf16x8 vf[2][8], vn[2][8];
; #pragma unroll
;         for (int a = 0; a < 2; ++a)
; #pragma unroll
;           for (int ks = 0; ks < 8; ++ks) vf[a][ks] = (bf16x8){0, 0, 0, 0, 0, 0, 0, 0};
;         int stepc = 0;
;         auto psteps = [&](const int j, auto ownc) {
;           constexpr bool own = decltype(ownc)::value;
;           const int n = j < 0 ? 0 : (own ? 256 : cnt[j]), ntile = (n + 15) >> 4;
;           for (int s0 = 0; s0 < ntile; s0 += 2, ++stepc) {
;             const LAS unsigned char* pbuf = Pb + (stepc & 1) * 16384;
;             const int tile = s0 + ptt;
;             if (tile < ntile && !(mode & 8)) {
;               const int rem = n - tile * 16;
;               const bool qv = fr < rem;
;               const int qidx = own ? tile * 16 + fr : (int)list[j * 256 + tile * 16 + (qv ? fr : 0)];
;               u32x4 pw[8];
; #pragma unroll
;               for (int ks = 0; ks < 8; ++ks) pw[ks] = *(const LAS u32x4*)(pbuf + ptt * 8192 + ks * 1024 + lane * 16);
;               LAS f32x4* op0 = (LAS f32x4*)(oacc + mo_oidx(qidx, dh * 8 + fq)); LAS f32x4* op1 = (LAS f32x4*)(oacc + mo_oidx(qidx, dh * 8 + 4 + fq));
;               const f32x4 a0 = *op0, a1 = *op1; const float al = lsl[qidx];
;               __builtin_amdgcn_sched_barrier(0);
;               f32x4 o0 = {0.f, 0.f, 0.f, 0.f}, o1 = {0.f, 0.f, 0.f, 0.f}, ol = {0.f, 0.f, 0.f, 0.f};
;               const bf16x8 ones = {0x3F80, 0x3F80, 0x3F80, 0x3F80, 0x3F80, 0x3F80, 0x3F80, 0x3F80};
; #pragma unroll
;               for (int ks = 0; ks < 8; ++ks) {
;                 const bf16x8 pb = __builtin_bit_cast(bf16x8, pw[ks]);
;                 o0 = MFMA16(vf[0][ks], pb, o0); o1 = MFMA16(vf[1][ks], pb, o1);
;                 if (dh == 0) ol = MFMA16(ones, pb, ol);
;               }
;               if (qv) {
;                 *op0 = a0 + o0; *op1 = a1 + o1;
;                 if (dh == 0 && fq == 0) lsl[qidx] = al + ol[0];
;               }
;             }
;             MO_BARRIER;
;           }
;         };
;         bool first = true;
;         for (int j = -1; j < blk; ++j) {
;           {
;             const bf16_t* vp = Mvt + vrow + ((long)(j + 1) * 64 + dh * 32 + fr) * 256 + fq * 8;
; #pragma unroll
;             for (int a = 0; a < 2; ++a)
; #pragma unroll
.LBB0_589:
	s_mov_b64 s[16:17], -1
	s_and_b64 vcc, exec, s[42:43]
	s_waitcnt lgkmcnt(0)
	s_barrier
	s_cbranch_vccz .LBB0_651
	s_cmp_lt_i32 s18, 0
	s_cselect_b64 s[54:55], -1, 0
	s_cmp_gt_i32 s18, -1
	s_mov_b32 s16, 0
	s_cselect_b64 s[52:53], -1, 0
	s_and_b64 vcc, exec, s[54:55]
	s_cbranch_vccnz .LBB0_623
	s_lshl_b64 s[14:15], s[14:15], 20
	v_mov_b32_e32 v68, 0
	v_lshl_add_u64 v[200:201], v[196:197], 0, s[14:15]
	s_mov_b32 s99, 0
	s_mov_b32 s100, 0x1000
	s_mov_b32 s101, 0
	s_mov_b64 s[14:15], -1
	s_mov_b32 s17, -1
	s_mov_b32 s19, s70
	v_mov_b32_e32 v69, v68
	v_mov_b32_e32 v70, v68
	v_mov_b32_e32 v71, v68
	v_mov_b32_e32 v72, v68
	v_mov_b32_e32 v73, v68
	v_mov_b32_e32 v74, v68
	v_mov_b32_e32 v75, v68
	v_mov_b32_e32 v76, v68
	v_mov_b32_e32 v77, v68
	v_mov_b32_e32 v78, v68
	v_mov_b32_e32 v79, v68
	v_mov_b32_e32 v80, v68
	v_mov_b32_e32 v81, v68
	v_mov_b32_e32 v82, v68
	v_mov_b32_e32 v83, v68
	v_mov_b32_e32 v84, v68
	v_mov_b32_e32 v85, v68
	v_mov_b32_e32 v86, v68
	v_mov_b32_e32 v87, v68
	v_mov_b32_e32 v88, v68
	v_mov_b32_e32 v89, v68
	v_mov_b32_e32 v90, v68
	v_mov_b32_e32 v91, v68
	v_mov_b32_e32 v92, v68
	v_mov_b32_e32 v93, v68
	v_mov_b32_e32 v94, v68
	v_mov_b32_e32 v95, v68
	v_mov_b32_e32 v96, v68
	v_mov_b32_e32 v97, v68
	v_mov_b32_e32 v98, v68
	v_mov_b32_e32 v99, v68
	v_mov_b32_e32 v100, v68
	v_mov_b32_e32 v101, v68
	v_mov_b32_e32 v102, v68
	v_mov_b32_e32 v103, v68
	v_mov_b32_e32 v104, v68
	v_mov_b32_e32 v105, v68
	v_mov_b32_e32 v106, v68
	v_mov_b32_e32 v107, v68
	v_mov_b32_e32 v108, v68
	v_mov_b32_e32 v109, v68
	v_mov_b32_e32 v110, v68
	v_mov_b32_e32 v111, v68
	v_mov_b32_e32 v112, v68
	v_mov_b32_e32 v113, v68
	v_mov_b32_e32 v114, v68
	v_mov_b32_e32 v115, v68
	v_mov_b32_e32 v116, v68
	v_mov_b32_e32 v117, v68
	v_mov_b32_e32 v118, v68
	v_mov_b32_e32 v119, v68
	v_mov_b32_e32 v120, v68
	v_mov_b32_e32 v121, v68
	v_mov_b32_e32 v122, v68
	v_mov_b32_e32 v123, v68
	v_mov_b32_e32 v124, v68
	v_mov_b32_e32 v125, v68
	v_mov_b32_e32 v126, v68
	v_mov_b32_e32 v127, v68
	v_mov_b32_e32 v128, v68
	v_mov_b32_e32 v129, v68
	v_mov_b32_e32 v130, v68
	v_mov_b32_e32 v131, v68
.LBB0_592:
	s_add_i32 s56, s17, 1
	s_ashr_i32 s57, s56, 31
	s_lshl_b64 s[22:23], s[56:57], 15
	v_lshl_add_u64 v[252:253], v[200:201], 0, s[22:23]
	s_mov_b32 s99, 1
	s_andn2_b64 vcc, exec, s[14:15]
	s_cbranch_vccz .LBB0_596
	s_cmp_lt_i32 s17, 0
	s_mov_b32 s14, 0
	s_cbranch_scc0 .LBB0_597

;     ...
;             const bf16_t* vp = Mvt + vrow + ((long)(j + 1) * 64 + dh * 32 + fr) * 256 + fq * 8;
; #pragma unroll
;             for (int a = 0; a < 2; ++a)
; #pragma unroll
;               for (int ks = 0; ks < 8; ++ks) vn[a][ks] = *(const bf16x8*)(vp + a * 16 * 256 + ks * 32);
.LBB0_595:
	s_cmp_eq_u32 s99, 0
	s_cbranch_scc1 .Lpvil_nfa
	global_load_dwordx4 v[32:35], v[252:253], off
	global_load_dwordx4 v[40:43], v[252:253], off offset:1024
	global_load_dwordx4 v[44:47], v[252:253], off offset:2048
	global_load_dwordx4 v[48:51], v[252:253], off offset:3072
	v_lshl_add_u64 v[254:255], v[252:253], 0, s[100:101]
	global_load_dwordx4 v[52:55], v[254:255], off
	global_load_dwordx4 v[56:59], v[254:255], off offset:1024
	global_load_dwordx4 v[60:63], v[254:255], off offset:2048
	global_load_dwordx4 v[64:67], v[254:255], off offset:3072
	v_lshl_add_u64 v[254:255], v[254:255], 0, s[100:101]
	global_load_dwordx4 v[36:39], v[254:255], off
	global_load_dwordx4 v[28:31], v[254:255], off offset:1024
	global_load_dwordx4 v[24:27], v[254:255], off offset:2048
	global_load_dwordx4 v[20:23], v[254:255], off offset:3072
	v_lshl_add_u64 v[254:255], v[254:255], 0, s[100:101]
	global_load_dwordx4 v[16:19], v[254:255], off
	global_load_dwordx4 v[12:15], v[254:255], off offset:1024
	global_load_dwordx4 v[8:11], v[254:255], off offset:2048
	global_load_dwordx4 v[4:7], v[254:255], off offset:3072
	s_mov_b32 s99, 0

; #define LAS __attribute__((address_space(3)))
; #define MFMA16(a, b, c) __builtin_amdgcn_mfma_f32_16x16x32_bf16((a), (b), (c), 0, 0, 0)
;     ...
;             if (tile < ntile && !(mode & 8)) {
;               const int rem = n - tile * 16;
;               const bool qv = fr < rem;
;               const int qidx = own ? tile * 16 + fr : (int)list[j * 256 + tile * 16 + (qv ? fr : 0)];
;               u32x4 pw[8];
; #pragma unroll
;               for (int ks = 0; ks < 8; ++ks) pw[ks] = *(const LAS u32x4*)(pbuf + ptt * 8192 + ks * 1024 + lane * 16);
;               LAS f32x4* op0 = (LAS f32x4*)(oacc + mo_oidx(qidx, dh * 8 + fq)); LAS f32x4* op1 = (LAS f32x4*)(oacc + mo_oidx(qidx, dh * 8 + 4 + fq));
;               const f32x4 a0 = *op0, a1 = *op1; const float al = lsl[qidx];
;               __builtin_amdgcn_sched_barrier(0);
;               f32x4 o0 = {0.f, 0.f, 0.f, 0.f}, o1 = {0.f, 0.f, 0.f, 0.f}, ol = {0.f, 0.f, 0.f, 0.f};
;               const bf16x8 ones = {0x3F80, 0x3F80, 0x3F80, 0x3F80, 0x3F80, 0x3F80, 0x3F80, 0x3F80};
; #pragma unroll
;               for (int ks = 0; ks < 8; ++ks) {
;                 const bf16x8 pb = __builtin_bit_cast(bf16x8, pw[ks]);
;                 o0 = MFMA16(vf[0][ks], pb, o0); o1 = MFMA16(vf[1][ks], pb, o1);
;                 if (dh == 0) ol = MFMA16(ones, pb, ol);
;               }
;     ...
;             const bf16_t* vp = Mvt + vrow + ((long)(j + 1) * 64 + dh * 32 + fr) * 256 + fq * 8;
; #pragma unroll
;             for (int a = 0; a < 2; ++a)
; #pragma unroll
;               for (int ks = 0; ks < 8; ++ks) vn[a][ks] = *(const bf16x8*)(vp + a * 16 * 256 + ks * 32);
.LBB0_601:
	s_cmp_ge_i32 s74, s30
	s_cbranch_scc1 .LBB0_600
	v_cmp_gt_i32_e64 s[14:15], s57, v193
	s_and_b32 s16, s39, 0x4000
	v_add_u32_e32 v2, s16, v206
	v_cndmask_b32_e64 v1, 0, v193, s[14:15]
	v_add_u32_e32 v1, s79, v1
	ds_read_u8 v1, v1
	ds_read_b128 v[168:171], v2 offset:1024
	ds_read_b128 v[164:167], v2 offset:2048
	ds_read_b128 v[160:163], v2 offset:3072
	ds_read_b128 v[156:159], v2 offset:4096
	ds_read_b128 v[152:155], v2 offset:5120
	ds_read_b128 v[148:151], v2 offset:6144
	ds_read_b128 v[144:147], v2 offset:7168
	s_waitcnt lgkmcnt(7)
	v_bitop3_b32 v3, v1, v205, 15 bitop3:0x6c
	v_lshlrev_b32_e32 v3, 4, v3
	v_lshlrev_b32_e32 v132, 8, v1
	v_add3_u32 v249, 0, v3, v132
	v_bitop3_b32 v3, v1, v207, 15 bitop3:0x6c
	v_lshlrev_b32_e32 v3, 4, v3
	v_lshl_add_u32 v1, v1, 2, 0
	v_add3_u32 v248, 0, v3, v132
	ds_read_b128 v[140:143], v249
	ds_read_b128 v[132:135], v248
	v_add_u32_e32 v246, 0x10000, v1
	ds_read_b128 v[172:175], v2
	ds_read_b32 v247, v246
	s_waitcnt lgkmcnt(1)
	v_mov_b32_e32 v136, 0
	v_mov_b32_e32 v137, 0
	v_mov_b32_e32 v138, 0
	v_mov_b32_e32 v139, 0
	v_mov_b32_e32 v1, v0
	v_mov_b32_e32 v2, v0
	v_mov_b32_e32 v3, v0
	s_andn2_b64 vcc, exec, s[44:45]
	s_cbranch_vccnz .Lpvil_dh1
	s_cmp_eq_u32 s99, 0
	s_cbranch_scc1 .Lpvil_o0
	v_mfma_f32_16x16x32_bf16 v[176:179], v[96:99], v[172:175], 0
	v_mfma_f32_16x16x32_bf16 v[180:183], v[100:103], v[172:175], 0
	v_mfma_f32_16x16x32_bf16 v[136:139], v[0:3], v[172:175], 0
	global_load_dwordx4 v[32:35], v[252:253], off
	global_load_dwordx4 v[40:43], v[252:253], off offset:1024
	v_mfma_f32_16x16x32_bf16 v[172:175], v[92:95], v[168:171], v[176:179]
	v_mfma_f32_16x16x32_bf16 v[176:179], v[104:107], v[168:171], v[180:183]
	v_mfma_f32_16x16x32_bf16 v[136:139], v[0:3], v[168:171], v[136:139]
	global_load_dwordx4 v[44:47], v[252:253], off offset:2048
	global_load_dwordx4 v[48:51], v[252:253], off offset:3072
	v_mfma_f32_16x16x32_bf16 v[168:171], v[88:91], v[164:167], v[172:175]
	v_mfma_f32_16x16x32_bf16 v[172:175], v[108:111], v[164:167], v[176:179]
	v_mfma_f32_16x16x32_bf16 v[136:139], v[0:3], v[164:167], v[136:139]
	v_lshl_add_u64 v[254:255], v[252:253], 0, s[100:101]
	global_load_dwordx4 v[52:55], v[254:255], off
	global_load_dwordx4 v[56:59], v[254:255], off offset:1024
	v_mfma_f32_16x16x32_bf16 v[164:167], v[84:87], v[160:163], v[168:171]
	v_mfma_f32_16x16x32_bf16 v[168:171], v[112:115], v[160:163], v[172:175]
	v_mfma_f32_16x16x32_bf16 v[136:139], v[0:3], v[160:163], v[136:139]
	global_load_dwordx4 v[60:63], v[254:255], off offset:2048
	global_load_dwordx4 v[64:67], v[254:255], off offset:3072
	v_mfma_f32_16x16x32_bf16 v[160:163], v[80:83], v[156:159], v[164:167]
	v_mfma_f32_16x16x32_bf16 v[164:167], v[116:119], v[156:159], v[168:171]
	v_mfma_f32_16x16x32_bf16 v[136:139], v[0:3], v[156:159], v[136:139]
	v_lshl_add_u64 v[254:255], v[254:255], 0, s[100:101]
	global_load_dwordx4 v[36:39], v[254:255], off
	global_load_dwordx4 v[28:31], v[254:255], off offset:1024
	v_mfma_f32_16x16x32_bf16 v[156:159], v[76:79], v[152:155], v[160:163]
	v_mfma_f32_16x16x32_bf16 v[160:163], v[120:123], v[152:155], v[164:167]
	v_mfma_f32_16x16x32_bf16 v[136:139], v[0:3], v[152:155], v[136:139]
	global_load_dwordx4 v[24:27], v[254:255], off offset:2048
	global_load_dwordx4 v[20:23], v[254:255], off offset:3072
	v_mfma_f32_16x16x32_bf16 v[152:155], v[72:75], v[148:151], v[156:159]
	v_mfma_f32_16x16x32_bf16 v[156:159], v[124:127], v[148:151], v[160:163]
	v_mfma_f32_16x16x32_bf16 v[136:139], v[0:3], v[148:151], v[136:139]
	v_lshl_add_u64 v[254:255], v[254:255], 0, s[100:101]
	global_load_dwordx4 v[16:19], v[254:255], off
	global_load_dwordx4 v[12:15], v[254:255], off offset:1024
	v_mfma_f32_16x16x32_bf16 v[152:155], v[68:71], v[144:147], v[152:155]
	v_mfma_f32_16x16x32_bf16 v[148:151], v[128:131], v[144:147], v[156:159]
	v_mfma_f32_16x16x32_bf16 v[136:139], v[0:3], v[144:147], v[136:139]
	global_load_dwordx4 v[8:11], v[254:255], off offset:2048
	global_load_dwordx4 v[4:7], v[254:255], off offset:3072
	s_mov_b32 s99, 0
	s_branch .Lpvil_tail
; #define MFMA16(a, b, c) __builtin_amdgcn_mfma_f32_16x16x32_bf16((a), (b), (c), 0, 0, 0)
;     ...
;               f32x4 o0 = {0.f, 0.f, 0.f, 0.f}, o1 = {0.f, 0.f, 0.f, 0.f}, ol = {0.f, 0.f, 0.f, 0.f};
;               const bf16x8 ones = {0x3F80, 0x3F80, 0x3F80, 0x3F80, 0x3F80, 0x3F80, 0x3F80, 0x3F80};
; #pragma unroll
;               for (int ks = 0; ks < 8; ++ks) {
;                 const bf16x8 pb = __builtin_bit_cast(bf16x8, pw[ks]);
;                 o0 = MFMA16(vf[0][ks], pb, o0); o1 = MFMA16(vf[1][ks], pb, o1);
;                 if (dh == 0) ol = MFMA16(ones, pb, ol);
;               }
;               if (qv) {
;                 *op0 = a0 + o0; *op1 = a1 + o1;
;                 if (dh == 0 && fq == 0) lsl[qidx] = al + ol[0];
;               }
.Lpvil_o0:
	v_mfma_f32_16x16x32_bf16 v[176:179], v[96:99], v[172:175], 0
	v_mfma_f32_16x16x32_bf16 v[180:183], v[100:103], v[172:175], 0
	v_mfma_f32_16x16x32_bf16 v[136:139], v[0:3], v[172:175], 0
	v_mfma_f32_16x16x32_bf16 v[172:175], v[92:95], v[168:171], v[176:179]
	v_mfma_f32_16x16x32_bf16 v[176:179], v[104:107], v[168:171], v[180:183]
	v_mfma_f32_16x16x32_bf16 v[136:139], v[0:3], v[168:171], v[136:139]
	v_mfma_f32_16x16x32_bf16 v[168:171], v[88:91], v[164:167], v[172:175]
	v_mfma_f32_16x16x32_bf16 v[172:175], v[108:111], v[164:167], v[176:179]
	v_mfma_f32_16x16x32_bf16 v[136:139], v[0:3], v[164:167], v[136:139]
	v_mfma_f32_16x16x32_bf16 v[164:167], v[84:87], v[160:163], v[168:171]
	v_mfma_f32_16x16x32_bf16 v[168:171], v[112:115], v[160:163], v[172:175]
	v_mfma_f32_16x16x32_bf16 v[136:139], v[0:3], v[160:163], v[136:139]
	v_mfma_f32_16x16x32_bf16 v[160:163], v[80:83], v[156:159], v[164:167]
	v_mfma_f32_16x16x32_bf16 v[164:167], v[116:119], v[156:159], v[168:171]
	v_mfma_f32_16x16x32_bf16 v[136:139], v[0:3], v[156:159], v[136:139]
	v_mfma_f32_16x16x32_bf16 v[156:159], v[76:79], v[152:155], v[160:163]
	v_mfma_f32_16x16x32_bf16 v[160:163], v[120:123], v[152:155], v[164:167]
	v_mfma_f32_16x16x32_bf16 v[136:139], v[0:3], v[152:155], v[136:139]
	v_mfma_f32_16x16x32_bf16 v[152:155], v[72:75], v[148:151], v[156:159]
	v_mfma_f32_16x16x32_bf16 v[156:159], v[124:127], v[148:151], v[160:163]
	v_mfma_f32_16x16x32_bf16 v[136:139], v[0:3], v[148:151], v[136:139]
	v_mfma_f32_16x16x32_bf16 v[152:155], v[68:71], v[144:147], v[152:155]
	v_mfma_f32_16x16x32_bf16 v[148:151], v[128:131], v[144:147], v[156:159]
	v_mfma_f32_16x16x32_bf16 v[136:139], v[0:3], v[144:147], v[136:139]
	s_branch .Lpvil_tail
.Lpvil_dh1:
	s_cmp_eq_u32 s99, 0
	s_cbranch_scc1 .Lpvil_p0
	v_mfma_f32_16x16x32_bf16 v[176:179], v[96:99], v[172:175], 0
	v_mfma_f32_16x16x32_bf16 v[180:183], v[100:103], v[172:175], 0
	global_load_dwordx4 v[32:35], v[252:253], off
	global_load_dwordx4 v[40:43], v[252:253], off offset:1024
	v_mfma_f32_16x16x32_bf16 v[172:175], v[92:95], v[168:171], v[176:179]
	v_mfma_f32_16x16x32_bf16 v[176:179], v[104:107], v[168:171], v[180:183]
	global_load_dwordx4 v[44:47], v[252:253], off offset:2048
	global_load_dwordx4 v[48:51], v[252:253], off offset:3072
	v_mfma_f32_16x16x32_bf16 v[168:171], v[88:91], v[164:167], v[172:175]
	v_mfma_f32_16x16x32_bf16 v[172:175], v[108:111], v[164:167], v[176:179]
	v_lshl_add_u64 v[254:255], v[252:253], 0, s[100:101]
	global_load_dwordx4 v[52:55], v[254:255], off
	global_load_dwordx4 v[56:59], v[254:255], off offset:1024
	v_mfma_f32_16x16x32_bf16 v[164:167], v[84:87], v[160:163], v[168:171]
	v_mfma_f32_16x16x32_bf16 v[168:171], v[112:115], v[160:163], v[172:175]
	global_load_dwordx4 v[60:63], v[254:255], off offset:2048
	global_load_dwordx4 v[64:67], v[254:255], off offset:3072
	v_mfma_f32_16x16x32_bf16 v[160:163], v[80:83], v[156:159], v[164:167]
	v_mfma_f32_16x16x32_bf16 v[164:167], v[116:119], v[156:159], v[168:171]
	v_lshl_add_u64 v[254:255], v[254:255], 0, s[100:101]
	global_load_dwordx4 v[36:39], v[254:255], off
	global_load_dwordx4 v[28:31], v[254:255], off offset:1024
	v_mfma_f32_16x16x32_bf16 v[156:159], v[76:79], v[152:155], v[160:163]
	v_mfma_f32_16x16x32_bf16 v[160:163], v[120:123], v[152:155], v[164:167]
	global_load_dwordx4 v[24:27], v[254:255], off offset:2048
	global_load_dwordx4 v[20:23], v[254:255], off offset:3072
	v_mfma_f32_16x16x32_bf16 v[152:155], v[72:75], v[148:151], v[156:159]
	v_mfma_f32_16x16x32_bf16 v[156:159], v[124:127], v[148:151], v[160:163]
	v_lshl_add_u64 v[254:255], v[254:255], 0, s[100:101]
	global_load_dwordx4 v[16:19], v[254:255], off
	global_load_dwordx4 v[12:15], v[254:255], off offset:1024
	v_mfma_f32_16x16x32_bf16 v[152:155], v[68:71], v[144:147], v[152:155]
	v_mfma_f32_16x16x32_bf16 v[148:151], v[128:131], v[144:147], v[156:159]
	global_load_dwordx4 v[8:11], v[254:255], off offset:2048
	global_load_dwordx4 v[4:7], v[254:255], off offset:3072
	s_mov_b32 s99, 0
	s_branch .Lpvil_tail
.Lpvil_p0:
	v_mfma_f32_16x16x32_bf16 v[176:179], v[96:99], v[172:175], 0
	v_mfma_f32_16x16x32_bf16 v[180:183], v[100:103], v[172:175], 0
	v_mfma_f32_16x16x32_bf16 v[172:175], v[92:95], v[168:171], v[176:179]
	v_mfma_f32_16x16x32_bf16 v[176:179], v[104:107], v[168:171], v[180:183]
	v_mfma_f32_16x16x32_bf16 v[168:171], v[88:91], v[164:167], v[172:175]
	v_mfma_f32_16x16x32_bf16 v[172:175], v[108:111], v[164:167], v[176:179]
	v_mfma_f32_16x16x32_bf16 v[164:167], v[84:87], v[160:163], v[168:171]
	v_mfma_f32_16x16x32_bf16 v[168:171], v[112:115], v[160:163], v[172:175]
	v_mfma_f32_16x16x32_bf16 v[160:163], v[80:83], v[156:159], v[164:167]
	v_mfma_f32_16x16x32_bf16 v[164:167], v[116:119], v[156:159], v[168:171]
	v_mfma_f32_16x16x32_bf16 v[156:159], v[76:79], v[152:155], v[160:163]
	v_mfma_f32_16x16x32_bf16 v[160:163], v[120:123], v[152:155], v[164:167]
	v_mfma_f32_16x16x32_bf16 v[152:155], v[72:75], v[148:151], v[156:159]
	v_mfma_f32_16x16x32_bf16 v[156:159], v[124:127], v[148:151], v[160:163]
	v_mfma_f32_16x16x32_bf16 v[152:155], v[68:71], v[144:147], v[152:155]
	v_mfma_f32_16x16x32_bf16 v[148:151], v[128:131], v[144:147], v[156:159]
.Lpvil_tail:
	s_nop 7

; __global__ void __launch_bounds__(NTHREADS) fwd_megakernel(Params p) {
	.amdhsa_kernel _Z14fwd_megakernel6Params
		.amdhsa_group_segment_fixed_size 0
		.amdhsa_private_segment_fixed_size 0
		.amdhsa_kernarg_size 368
		.amdhsa_user_sgpr_count 2
		.amdhsa_user_sgpr_dispatch_ptr 0
		.amdhsa_user_sgpr_queue_ptr 0
		.amdhsa_user_sgpr_kernarg_segment_ptr 1
		.amdhsa_user_sgpr_dispatch_id 0
		.amdhsa_user_sgpr_kernarg_preload_length 0
		.amdhsa_user_sgpr_kernarg_preload_offset 0
		.amdhsa_user_sgpr_private_segment_size 0
		.amdhsa_uses_dynamic_stack 0
		.amdhsa_enable_private_segment 0
		.amdhsa_system_sgpr_workgroup_id_x 1
		.amdhsa_system_sgpr_workgroup_id_y 0
		.amdhsa_system_sgpr_workgroup_id_z 0
		.amdhsa_system_sgpr_workgroup_info 0
		.amdhsa_system_vgpr_workitem_id 2
		.amdhsa_next_free_vgpr 256
		.amdhsa_next_free_sgpr 102
		.amdhsa_accum_offset 256
		.amdhsa_reserve_vcc 1
		.amdhsa_float_round_mode_32 0
		.amdhsa_float_round_mode_16_64 0
		.amdhsa_float_denorm_mode_32 3
		.amdhsa_float_denorm_mode_16_64 3
		.amdhsa_dx10_clamp 1
		.amdhsa_ieee_mode 1
		.amdhsa_fp16_overflow 0
		.amdhsa_tg_split 0
		.amdhsa_exception_fp_ieee_invalid_op 0
		.amdhsa_exception_fp_denorm_src 0
		.amdhsa_exception_fp_ieee_div_zero 0
		.amdhsa_exception_fp_ieee_overflow 0
		.amdhsa_exception_fp_ieee_underflow 0
		.amdhsa_exception_fp_ieee_inexact 0
		.amdhsa_exception_int_div_zero 0
	.end_amdhsa_kernel

; __global__ void __launch_bounds__(NTHREADS) fwd_megakernel(Params p) {
amdhsa.kernels:
  - .agpr_count:     0
    .args:
      - .offset:         0
        .size:           112
        .value_kind:     by_value
      - .offset:         112
        .size:           4
        .value_kind:     hidden_block_count_x
      - .offset:         116
        .size:           4
        .value_kind:     hidden_block_count_y
      - .offset:         120
        .size:           4
        .value_kind:     hidden_block_count_z
      - .offset:         124
        .size:           2
        .value_kind:     hidden_group_size_x
      - .offset:         126
        .size:           2
        .value_kind:     hidden_group_size_y
      - .offset:         128
        .size:           2
        .value_kind:     hidden_group_size_z
      - .offset:         130
        .size:           2
        .value_kind:     hidden_remainder_x
      - .offset:         132
        .size:           2
        .value_kind:     hidden_remainder_y
      - .offset:         134
        .size:           2
        .value_kind:     hidden_remainder_z
      - .offset:         152
        .size:           8
        .value_kind:     hidden_global_offset_x
      - .offset:         160
        .size:           8
        .value_kind:     hidden_global_offset_y
      - .offset:         168
        .size:           8
        .value_kind:     hidden_global_offset_z
      - .offset:         176
        .size:           2
        .value_kind:     hidden_grid_dims
      - .offset:         200
        .size:           8
        .value_kind:     hidden_multigrid_sync_arg
      - .offset:         232
        .size:           4
        .value_kind:     hidden_dynamic_lds_size
    .group_segment_fixed_size: 0
    .kernarg_segment_align: 8
    .kernarg_segment_size: 368
    .language:       OpenCL C
    .language_version:
      - 2
      - 0
    .max_flat_workgroup_size: 512
    .name:           _Z14fwd_megakernel6Params
    .private_segment_fixed_size: 0
    .sgpr_count:     108
    .sgpr_spill_count: 7
    .symbol:         _Z14fwd_megakernel6Params.kd
    .uniform_work_group_size: 1
    .uses_dynamic_stack: false
    .vgpr_count:     256
    .vgpr_spill_count: 0
    .wavefront_size: 64
